# A1/A3 work queues: first item statically = workgroup id (no atomic stampede, one barrier pair fewer), later pops offset by 256
# speedup vs baseline: 1.0084x; 1.0040x over previous
; template <int DQK, int MODE> ...
;     ...
;     const int tid = fresh_tid2(wv0), lane = tid & 63, wid = wv0, r32 = lane & 31, hi = lane >> 5;
;     const int qpos = q0 + 32 * wid + r32, qmin = q0 + 32 * wid, qmax = qmin + 31;
;     bf16x8 qf[NKS];
; #pragma unroll
;     for (int ks = 0; ks < NKS; ++ks) qf[ks] = *(const bf16x8*)(Qp + (size_t)(32 * wid + r32) * qpitch + 16 * ks + 8 * hi);
;     if (DQK == 96) {
; #pragma unroll
;         for (int ks = 4; ks < NKS; ++ks) {
;             const int p0 = 8 * (ks - 4) + 4 * hi;
;             const f32x4 c4 = *(const f32x4*)(rope + ROPE_MLA_COS + qpos * 16 + p0), s4 = *(const f32x4*)(rope + ROPE_MLA_SIN + qpos * 16 + p0);
;             u32x4 w = __builtin_bit_cast(u32x4, qf[ks]);
; #pragma unroll
;             for (int k = 0; k < 4; ++k) { const float x1 = bflo(w[k]), x2 = bfhi(w[k]); w[k] = cvtpk(x1 * c4[k] - x2 * s4[k], x2 * c4[k] + x1 * s4[k]); }
;             qf[ks] = __builtin_bit_cast(bf16x8, w);
;         }
;     }
; #pragma unroll
;     for (int ks = 0; ks < NKS; ++ks) asm volatile("" : "+v"(qf[ks]));
;     f32x16 o[2]; o[0] = (f32x16){}; o[1] = (f32x16){};
;     float mref = -1e30f, l = 0.f;
;     const int srow = tid >> 3, sch = tid & 7, srow2 = tid >> 2, sch2 = tid & 3;
;     u32x4 rk1, rk2 = (u32x4){}, rv;
; __global__ void __launch_bounds__(512) mega_fwd(Params P) {
;     ...
;             for (;;) {
;                 __syncthreads();
;                 if (tid == 0) *s_item = (int)atomicAdd(ctr, 1u);
;                 __syncthreads();
;                 const int it = *s_item;
;                 if (it >= 384) break;
;                 const int qb = 31 - it / 12, bh = it % 12, b = bh / 6, h = bh % 6, g = h / 3, q0 = qb * 256;
;                 const size_t rb = (size_t)b * SEQ;
;                 const int cmax = (q0 + 224) >> 4, t1 = (cmax >> 6) + 1;
;                 const float gate = GATES[(rb + q0 + 32 * wid + r32) * 32 + h * 3 + 0];
;                 f32x16 tot[2]; tot[0] = (f32x16){}; tot[1] = (f32x16){};
;                 flash_unit<64, MODE_CMP>(lds, wv0, PROJ + (rb + q0) * NPROJ + PC_NQ + 64 * h, NPROJ, KCVC + ((size_t)(b * NCMP) * 2 + g) * 256, 512, nullptr, 0,
;                                          KCVC + ((size_t)2048 + (size_t)(b * NCMP) * 2 + g) * 256 + 64, 512, q0, 0, t1, 0.125f * LOG2E, (u32x4){}, gate, tot,
;                                          LSE + (size_t)(b * 6 + h) * SEQ + q0);
.LBB0_1072:
	s_or_b64 exec, exec, s[4:5]
	v_mov_b32_e32 v0, s16
	s_waitcnt lgkmcnt(0)
	s_barrier
	ds_read_b32 v0, v0
	s_movk_i32 s4, 0x7f
	s_waitcnt lgkmcnt(0)
	v_cmp_lt_i32_e32 vcc, s4, v0
	v_readfirstlane_b32 s6, v0
	s_mov_b64 s[4:5], -1
	s_nop 1
	s_addk_i32 s6, 0x100
	s_cbranch_vccnz .LBB0_1069
	s_branch .La1_item
.La1_first:
	s_mov_b32 s6, s75
	s_mov_b64 s[4:5], -1
.La1_item:
	s_mul_hi_i32 s4, s6, 0xd5555555
	s_lshr_b32 s5, s4, 31
	s_lshr_b32 s4, s4, 1
	s_add_i32 s5, s4, s5
	s_mul_hi_i32 s4, s6, 0x2aaaaaab
	s_lshr_b32 s7, s4, 31
	s_lshr_b32 s4, s4, 1
	s_add_i32 s4, s4, s7
	s_mul_i32 s4, s4, 12
	s_sub_i32 s6, s6, s4
	s_bfe_i32 s4, s6, 0x80000
	s_mul_i32 s4, s4, 43
	s_bfe_u32 s7, s4, 0x1000f
	s_bfe_u32 s4, s4, 0x80008
	s_add_i32 s4, s4, s7
	s_mul_i32 s7, s4, 6
	s_sub_i32 s6, s6, s7
	s_sext_i32_i8 s21, s6
	s_bfe_i32 s6, s6, 0x80000
	s_mulk_i32 s6, 0x56
	s_bfe_u32 s7, s6, 0x1000f
	s_bfe_u32 s6, s6, 0x80008
	s_lshl_b32 s24, s5, 8
	s_bfe_i64 s[12:13], s[4:5], 0x80000
	s_add_i32 s6, s6, s7
	s_add_i32 s28, s24, 0x1f00
	s_lshl_b64 s[12:13], s[12:13], 13
	s_addk_i32 s24, 0x1fe0
	s_add_u32 s12, s12, s28
	s_addc_u32 s13, s13, 0
	s_mul_i32 s22, s21, 3
	s_mul_i32 s5, s13, 0x1400
	s_mul_hi_u32 s7, s12, 0x1400
	s_ashr_i32 s23, s22, 31
	s_add_i32 s7, s7, s5
	s_mul_i32 s5, s12, 0x1400
	v_lshl_add_u64 v[126:127], s[12:13], 0, v[122:123]
	s_add_u32 s5, s14, s5
	v_lshlrev_b64 v[2:3], 7, v[126:127]
	s_addc_u32 s7, s15, s7
	s_lshl_b32 s12, s21, 6
	s_mov_b32 s29, s81
	v_lshl_add_u64 v[2:3], s[8:9], 0, v[2:3]
	s_ashr_i32 s13, s12, 31
	v_lshl_add_u64 v[2:3], s[22:23], 2, v[2:3]
	s_mov_b32 s22, s29
	s_lshl_b64 s[26:27], s[12:13], 1
	v_mov_b32_e32 v0, v1
	flat_load_dword v125, v[2:3]
	s_add_u32 s5, s5, s26
	s_addc_u32 s7, s7, s27
	v_mbcnt_lo_u32_b32 v0, -1, v0
	s_add_u32 s26, s5, 0x3c00340
	v_mbcnt_hi_u32_b32 v3, -1, v0
	s_addc_u32 s27, s7, 0
	v_and_b32_e32 v4, 31, v3
	v_readlane_b32 s5, v254, 6
	v_bfe_u32 v2, v3, 5, 1
	v_mov_b64_e32 v[6:7], s[26:27]
	v_or_b32_e32 v128, s5, v4
	v_mad_i64_i32 v[6:7], s[26:27], v128, s69, v[6:7]
	v_lshlrev_b32_e32 v0, 4, v2
	v_lshl_add_u64 v[6:7], v[6:7], 0, v[0:1]
	flat_load_dwordx4 v[66:69], v[6:7]
	flat_load_dwordx4 v[70:73], v[6:7] offset:32
	flat_load_dwordx4 v[74:77], v[6:7] offset:64
	flat_load_dwordx4 v[78:81], v[6:7] offset:96
	s_sext_i32_i8 s23, s4
	s_mul_i32 s4, s23, 0x1ff
	s_ashr_i32 s5, s4, 31
	s_bfe_i64 s[6:7], s[6:7], 0x80000
	s_lshl_b64 s[4:5], s[4:5], 10
	s_lshl_b64 s[6:7], s[6:7], 9
	s_add_u32 s4, s17, s4
	v_or_b32_e32 v0, s79, v3
	s_addc_u32 s5, s18, s5
	v_lshlrev_b32_e32 v5, 4, v3
	v_ashrrev_i32_e32 v7, 3, v0
	s_add_u32 s4, s4, s6
	v_and_b32_e32 v5, 0x70, v5
	v_lshlrev_b32_e32 v6, 10, v7
	s_addc_u32 s5, s5, s7
	v_or_b32_e32 v0, v6, v5
	s_add_u32 s6, s4, 0x100080
	v_lshl_add_u64 v[8:9], s[4:5], 0, v[0:1]
	s_addc_u32 s7, s5, 0
	v_lshl_add_u64 v[10:11], s[6:7], 0, v[0:1]
	s_movk_i32 s25, 0x90
	v_mul_lo_u32 v0, v7, s25
	s_mov_b64 s[80:81], s[28:29]
	v_add3_u32 v130, s22, v0, v5
	s_cmpk_lt_u32 s24, 0x400
	flat_load_dwordx4 v[82:85], v[8:9]
	flat_load_dwordx4 v[86:89], v[10:11]
	s_waitcnt vmcnt(0) lgkmcnt(0)
	s_waitcnt lgkmcnt(0)
	s_barrier
	s_waitcnt vmcnt(0)
	ds_write_b128 v130, v[82:85]
	ds_write_b128 v130, v[86:89] offset:28672
	s_cbranch_scc1 .LBB0_1075
	v_add3_u32 v0, v6, v5, s66
	v_lshl_add_u64 v[8:9], s[4:5], 0, v[0:1]
	v_lshl_add_u64 v[10:11], s[6:7], 0, v[0:1]
	flat_load_dwordx4 v[82:85], v[8:9]
	flat_load_dwordx4 v[86:89], v[10:11]

; #define GATES WSP(float, WS_GATES)
; __global__ void __launch_bounds__(512) mega_fwd(Params P) {
;     ...
;             for (;;) {
;                 __syncthreads();
;                 if (tid == 0) *s_item = (int)atomicAdd(ctr, 1u);
;                 __syncthreads();
;                 const int it = *s_item;
;                 if (it >= 1024) break;
;                 if (it >= 768) {
;                     const int k = it - 768, qb = 31 - k / 8, bh = k % 8, b = bh >> 2, h = bh & 3, q0 = qb * 256;
;                     const size_t rb = (size_t)b * SEQ;
;                     f32x16 tot[2]; tot[0] = (f32x16){}; tot[1] = (f32x16){};
;                     sb_unit(lds, wv0, PROJ + (rb + q0) * NPROJ + PC_SBQ + 64 * h, PROJ + rb * NPROJ + PC_SBK + 64 * h, PROJ + rb * NPROJ + PC_SBV + 64 * h, q0, tot);
;                     store_o(tot, HN + (rb + q0 + 32 * wid + r32) * DM + 768 + h * 64, hi);
;                     continue;
;                 }
;                 const int qb = 31 - it / 24, r24 = it % 24, bh = r24 % 12, b = bh / 6, h = bh % 6, g = h / 3, q0 = qb * 256;
;                 const size_t rb = (size_t)b * SEQ; const size_t qrow = rb + q0 + 32 * wid + r32;
;                 if (r24 < 12) {
;                     f32x16 tot[2]; tot[0] = (f32x16){}; tot[1] = (f32x16){};
;                     flash_unit<96, MODE_CAUSAL>(lds, wv0, QMLA + (rb + q0) * 576 + h * 96, 576, KVB + rb * 768 + h * 64, 768, PROJ + rb * NPROJ + PC_KR, NPROJ,
;                                                 KVB + rb * 768 + 384 + h * 64, 768, q0, 0, (q0 + 256) / 64, 0.10206207261596577f * LOG2E, (u32x4){}, 1.f, tot, nullptr, WSP(float, WS_ROPE));
;                     store_o(tot, HN + qrow * DM + h * 64, hi);
;                 } else {
;                     const float g1 = GATES[qrow * 32 + h * 3 + 1], g2 = GATES[qrow * 32 + h * 3 + 2];
;                     const u32x4 mw = *(const u32x4*)(MASKS + ((size_t)(b * 2 + g) * SEQ + q0 + 32 * wid + r32) * 4);
;                     f32x16 tot[2];
;                     { const bf16_t* oc = OCMP + qrow * 384 + h * 64;
; #pragma unroll
;                       for (int d0 = 0; d0 < 2; ++d0)
; #pragma unroll
;                           for (int j = 0; j < 4; ++j) { const u32x2 w = *(const u32x2*)(oc + 32 * d0 + 8 * j + 4 * hi); tot[d0][4 * j] = bflo(w.x); tot[d0][4 * j + 1] = bfhi(w.x); tot[d0][4 * j + 2] = bflo(w.y); tot[d0][4 * j + 3] = bfhi(w.y); } }
.LBB0_1306:
	s_or_b64 exec, exec, s[0:1]
	v_mov_b32_e32 v0, s38
	s_waitcnt lgkmcnt(0)
	s_barrier
	ds_read_b32 v0, v0
	s_movk_i32 s0, 0x2ff
	s_waitcnt lgkmcnt(0)
	v_cmp_lt_i32_e32 vcc, s0, v0
	v_readfirstlane_b32 s34, v0
	s_mov_b64 s[0:1], -1
	s_nop 1
	s_addk_i32 s34, 0x100
	s_cbranch_vccnz .LBB0_1303
	s_branch .La3_item
.La3_first:
	s_mov_b32 s34, s75
	s_mov_b64 s[0:1], -1
.La3_item:
	s_cmpk_lt_i32 s34, 0x300
	s_cbranch_scc0 .LBB0_1372
	s_mul_hi_i32 s0, s34, 0xd5555555
	s_lshr_b32 s1, s0, 31
	s_lshr_b32 s0, s0, 2
	s_add_i32 s4, s0, s1
	s_mul_hi_i32 s0, s34, 0x2aaaaaab
	s_lshr_b32 s1, s0, 31
	s_lshr_b32 s0, s0, 2
	s_add_i32 s0, s0, s1
	s_mul_i32 s0, s0, 24
	s_sub_i32 s6, s34, s0
	s_mul_i32 s0, s6, 43
	s_sext_i32_i16 s1, s0
	s_lshr_b32 s1, s1, 9
	s_bfe_u32 s0, s0, 0x1000f
	s_add_i32 s0, s1, s0
	s_mul_i32 s0, s0, 12
	s_sub_i32 s1, s6, s0
	s_bfe_i32 s0, s1, 0x80000
	s_mul_i32 s0, s0, 43
	s_bfe_u32 s5, s0, 0x1000f
	s_bfe_u32 s0, s0, 0x80008
	s_add_i32 s0, s0, s5
	s_mul_i32 s5, s0, 6
	s_sub_i32 s1, s1, s5
	s_lshl_b32 s35, s4, 8
	s_bfe_i64 s[8:9], s[0:1], 0x80000
	s_add_i32 s36, s35, 0x1f00
	s_lshl_b64 s[4:5], s[8:9], 13
	s_add_u32 s26, s4, s36
	s_addc_u32 s27, s5, 0
	s_sext_i32_i8 s37, s1
	v_lshl_add_u64 v[180:181], s[26:27], 0, v[174:175]
	s_mov_b64 s[4:5], -1
	s_cmp_gt_i32 s6, 11
	s_mul_hi_i32 s45, s8, 0x2800000
	s_mul_i32 s46, s8, 0x2800000
	s_cbranch_scc0 .LBB0_1346
	s_bfe_i32 s1, s1, 0x80000
	s_mulk_i32 s1, 0x56
	s_bfe_u32 s4, s1, 0x1000f
	s_bfe_u32 s1, s1, 0x80008
	s_add_i32 s1, s1, s4
	s_sext_i32_i8 s6, s1
	s_sext_i32_i8 s0, s0
	s_lshl_b32 s0, s0, 14
	s_lshl_b32 s1, s6, 13
	s_add_i32 s1, s1, s0
	s_add_u32 s0, s1, s36
	s_addc_u32 s1, 0, 0
	v_mov_b64_e32 v[6:7], s[18:19]
	v_lshl_add_u64 v[4:5], s[0:1], 0, v[174:175]
	v_mad_u64_u32 v[6:7], s[0:1], v180, s72, v[6:7]
	v_mov_b32_e32 v0, v7
	v_lshlrev_b64 v[2:3], 7, v[180:181]
	v_mad_u64_u32 v[8:9], s[0:1], v181, s72, v[0:1]
	s_mul_i32 s80, s37, 3
	v_lshl_add_u64 v[2:3], s[14:15], 0, v[2:3]
	s_mul_i32 s0, s27, 0x1400
	s_mul_hi_u32 s1, s26, 0x1400
	v_lshl_add_u64 v[2:3], s[80:81], 2, v[2:3]
	s_lshl_b32 s9, s37, 6
	s_lshl_b32 s80, s37, 7
	s_add_i32 s1, s1, s0
	s_mul_i32 s0, s26, 0x1400
	s_add_u32 s0, s39, s0
	v_mov_b32_e32 v7, v8
	s_addc_u32 s1, s40, s1
	v_lshl_add_u64 v[6:7], v[6:7], 0, s[80:81]
	v_mov_b32_e32 v179, v1
	s_add_u32 s30, s0, s80
	v_lshl_add_u64 v[4:5], v[4:5], 4, s[16:17]
	v_lshl_add_u64 v[6:7], v[6:7], 0, v[178:179]
	s_addc_u32 s31, s1, 0
	s_mov_b32 s1, s81
	v_mov_b32_e32 v0, v1
	flat_load_dwordx2 v[182:183], v[2:3] offset:4
	s_nop 0
	flat_load_dwordx4 v[2:5], v[4:5]
	s_nop 0
	flat_load_dwordx2 v[198:199], v[6:7]
	flat_load_dwordx2 v[196:197], v[6:7] offset:16
	flat_load_dwordx2 v[194:195], v[6:7] offset:32
	flat_load_dwordx2 v[192:193], v[6:7] offset:48
	flat_load_dwordx2 v[190:191], v[6:7] offset:64
	flat_load_dwordx2 v[188:189], v[6:7] offset:80
	flat_load_dwordx2 v[186:187], v[6:7] offset:96
	flat_load_dwordx2 v[184:185], v[6:7] offset:112
	v_readlane_b32 s7, v254, 6
	v_mbcnt_lo_u32_b32 v0, -1, v0
	v_mbcnt_hi_u32_b32 v26, -1, v0
	v_and_b32_e32 v27, 31, v26
	v_bfe_u32 v28, v26, 5, 1
	v_or_b32_e32 v0, s7, v27
	v_mov_b64_e32 v[6:7], s[30:31]
	v_mad_i64_i32 v[6:7], s[4:5], v0, s69, v[6:7]
	v_lshlrev_b32_e32 v0, 4, v28
	v_lshl_add_u64 v[6:7], v[6:7], 0, v[0:1]
	s_waitcnt vmcnt(0)
	flat_load_dwordx4 v[84:87], v[6:7] offset:832
	flat_load_dwordx4 v[80:83], v[6:7] offset:864
	flat_load_dwordx4 v[10:13], v[6:7] offset:896
	s_nop 0
	flat_load_dwordx4 v[6:9], v[6:7] offset:928
	s_add_u32 s0, s39, s46
	v_or_b32_e32 v14, s79, v26
	s_addc_u32 s4, s40, s45
	s_lshl_b32 s5, s6, 7
	v_and_b32_e32 v15, 7, v26
	v_ashrrev_i32_e32 v24, 3, v14
	s_add_u32 s28, s0, s5
	v_lshlrev_b32_e32 v29, 4, v15
	v_mul_lo_u32 v14, v24, s69
	v_mov_b32_e32 v23, v1
	s_addc_u32 s29, s4, 0
	v_or_b32_e32 v22, v29, v14
	v_lshl_add_u64 v[18:19], s[28:29], 0, v[22:23]
	s_movk_i32 s4, 0x90
	v_mul_lo_u32 v23, v24, s4
	v_mov_b32_e32 v25, v1
	v_add3_u32 v129, s1, v23, v29
	v_add_u32_e32 v24, 0x50000, v22
	v_lshl_add_u64 v[24:25], s[28:29], 0, v[24:25]
	v_add_u32_e32 v226, 0xa0000, v22
	v_mov_b32_e32 v227, v1
	v_lshl_add_u64 v[226:227], s[28:29], 0, v[226:227]
	v_add_u32_e32 v232, 0xf0000, v22
	v_mov_b32_e32 v233, v1
	v_lshl_add_u64 v[232:233], s[28:29], 0, v[232:233]
	v_mad_u32_u24 v131, v27, s4, v0
	v_lshlrev_b32_e32 v128, 2, v28
	v_lshrrev_b32_e32 v0, 2, v26
	s_add_i32 s0, s35, 0x2000
	s_add_i32 s48, s36, s7
	v_and_or_b32 v0, v0, 3, v128
	v_mov_b32_e32 v30, v1
	v_mov_b32_e32 v31, v1
	s_lshr_b32 s47, s0, 6
	v_mov_b32_e32 v23, v1
	v_mov_b32_e32 v28, v1
	v_mov_b32_e32 v29, v1
	s_mov_b32 s53, s81
	s_mov_b32 s50, 0
	s_or_b32 s49, s48, 31
	s_add_i32 s0, s47, -1
	v_mov_b32_e32 v179, 0
	s_mov_b32 s51, 63
	global_load_dwordx4 v[14:17], v[18:19], off offset:2112
	s_nop 0
	global_load_dwordx4 v[18:21], v[18:19], off offset:2368
	global_load_dwordx4 v[88:91], v[24:25], off offset:2368
	global_load_dwordx4 v[92:95], v[24:25], off offset:2112
	s_waitcnt vmcnt(0) lgkmcnt(0)
	s_waitcnt lgkmcnt(0)
	s_barrier
	s_waitcnt vmcnt(0)
	ds_write_b128 v129, v[14:17]
	ds_write_b128 v129, v[18:21] offset:36864
	v_add_u32_e32 v229, 0x2400, v129
	ds_write_b128 v229, v[92:95]
	ds_write_b128 v229, v[88:91] offset:36864
	global_load_dwordx4 v[88:91], v[226:227], off offset:2368
	global_load_dwordx4 v[92:95], v[226:227], off offset:2112
	global_load_dwordx4 v[222:225], v[232:233], off offset:2368
	global_load_dwordx4 v[218:221], v[232:233], off offset:2112
	v_lshlrev_b32_e32 v14, 1, v26
	v_and_b32_e32 v14, 32, v14
	v_lshlrev_b32_e32 v16, 3, v26
	v_and_or_b32 v14, v16, 24, v14
	v_or_b32_e32 v15, s48, v27
	v_mad_u32_u24 v130, v0, s4, v14
	v_add_u32_e32 v0, 0xf0000, v22
	v_mov_b32_e32 v16, v1
	v_mov_b32_e32 v17, v1
	v_mov_b32_e32 v18, v1
	v_mov_b32_e32 v19, v1
	v_mov_b32_e32 v20, v1
	v_mov_b32_e32 v21, v1
	v_mov_b32_e32 v22, v1
	v_mov_b32_e32 v24, v1
	v_mov_b32_e32 v25, v1
	v_mov_b32_e32 v26, v1
	v_mov_b32_e32 v27, v1
	v_mov_b64_e32 v[46:47], v[30:31]
	v_mov_b32_e32 v14, 0xf149f2ca
	v_mov_b64_e32 v[44:45], v[28:29]
	v_mov_b64_e32 v[42:43], v[26:27]
	v_mov_b64_e32 v[40:41], v[24:25]
	v_mov_b64_e32 v[38:39], v[22:23]
	v_mov_b64_e32 v[36:37], v[20:21]
	v_mov_b64_e32 v[34:35], v[18:19]
	v_mov_b64_e32 v[32:33], v[16:17]
	s_waitcnt lgkmcnt(0)
	s_barrier
	s_branch .LBB0_1311
